# P1+P6 GEMM epilogues: rs/ss loads hoisted to tile start, 8 serialized vmcnt(0) removed per tile
# speedup vs baseline: 1.0009x; 1.0009x over previous
.LBB0_94:
	v_lshl_add_u32 v228, s60, 8, v153
	v_lshlrev_b32_e32 v228, 2, v228
	global_load_dword v229, v228, s[92:93]
	global_load_dword v230, v228, s[92:93] offset:64
	global_load_dword v231, v228, s[92:93] offset:128
	global_load_dword v232, v228, s[92:93] offset:192
	global_load_dword v233, v228, s[92:93] offset:512
	global_load_dword v234, v228, s[92:93] offset:576
	global_load_dword v235, v228, s[92:93] offset:640
	global_load_dword v236, v228, s[92:93] offset:704
	s_add_i32 s19, s19, 1
	s_mul_i32 s2, s19, s22
	s_mul_hi_u32 s3, s19, s65
	s_add_i32 s3, s3, s2
	s_mul_i32 s2, s19, s65
	s_add_u32 s8, s2, s64
	s_addc_u32 s9, s3, s23
	v_cmp_gt_i64_e32 vcc, s[8:9], v[142:143]
	v_cmp_lt_i64_e64 s[2:3], s[8:9], v[140:141]
	s_cbranch_vccnz .LBB0_96
	s_ashr_i32 s5, s8, 31
	s_lshr_b32 s5, s5, 29
	s_add_i32 s5, s8, s5
	s_ashr_i32 s9, s5, 3
	s_and_b32 s5, s5, -8
	s_sub_i32 s5, s8, s5
	s_cmp_lt_i32 s5, 0
	s_cselect_b32 s8, s24, 0xa0
	s_mul_i32 s5, s5, s8
	s_add_i32 s5, s5, s9
	s_mul_hi_i32 s8, s5, 0x66666667
	s_lshr_b32 s9, s8, 31
	s_ashr_i32 s8, s8, 6
	s_add_i32 s8, s8, s9
	s_lshl_b32 s9, s8, 3
	s_sub_i32 s14, 64, s9
	s_min_i32 s15, s14, 8
	s_abs_i32 s14, s15
	v_cvt_f32_u32_e32 v0, s14
	s_sub_i32 s30, 0, s14
	s_mulk_i32 s8, 0xa0
	s_sub_i32 s5, s5, s8
	v_rcp_iflag_f32_e32 v0, v0
	s_abs_i32 s8, s5
	s_xor_b32 s29, s5, s15
	s_ashr_i32 s29, s29, 31
	v_mul_f32_e32 v0, 0x4f7ffffe, v0
	v_cvt_u32_f32_e32 v0, v0
	s_nop 0
	v_readfirstlane_b32 s31, v0
	s_mul_i32 s30, s30, s31
	s_mul_hi_u32 s30, s31, s30
	s_add_i32 s31, s31, s30
	s_mul_hi_u32 s30, s8, s31
	s_mul_i32 s31, s30, s14
	s_sub_i32 s8, s8, s31
	s_add_i32 s33, s30, 1
	s_sub_i32 s31, s8, s14
	s_cmp_ge_u32 s8, s14
	s_cselect_b32 s30, s33, s30
	s_cselect_b32 s8, s31, s8
	s_add_i32 s31, s30, 1
	s_cmp_ge_u32 s8, s14
	s_cselect_b32 s8, s31, s30
	s_xor_b32 s8, s8, s29
	s_sub_i32 s14, s8, s29
	s_mul_i32 s8, s14, s15
	s_sub_i32 s5, s5, s8
	s_add_i32 s34, s9, s5

.LBB0_100:
	v_lshl_add_u32 v146, s60, 8, v153
	v_ashrrev_i32_e32 v147, 31, v146
	v_lshl_add_u64 v[148:149], v[146:147], 2, s[92:93]
	v_mov_b32_e32 v150, v229
	v_lshl_or_b32 v144, s4, 8, v155
	v_cmp_gt_i32_e32 vcc, s27, v144
	v_ashrrev_i32_e32 v145, 31, v144
	v_mov_b32_e32 v151, v150
	s_and_saveexec_b64 s[4:5], vcc
	s_cbranch_execz .LBB0_102
	v_readlane_b32 s8, v246, 36
	v_mov_b32_e32 v160, v150
	v_mov_b32_e32 v161, v150
	v_pk_mul_f32 v[124:125], v[124:125], v[150:151]
	v_readlane_b32 s9, v246, 37
	v_pk_mul_f32 v[126:127], v[126:127], v[160:161]
	v_pk_mul_f32 v[160:161], v[122:123], v[160:161]
	v_pk_mul_f32 v[122:123], v[120:121], v[150:151]
	v_cvt_pk_bf16_f32 v120, v124, v125
	v_mov_b64_e32 v[124:125], s[8:9]
	v_mad_i64_i32 v[124:125], s[8:9], v146, s28, v[124:125]
	v_cvt_pk_bf16_f32 v121, v126, v127
	v_cvt_pk_bf16_f32 v122, v122, v123
	v_cvt_pk_bf16_f32 v123, v160, v161
	v_lshl_add_u64 v[124:125], v[144:145], 1, v[124:125]
	global_store_dwordx4 v[124:125], v[120:123], off

.LBB0_104:
	s_or_b64 exec, exec, s[8:9]
	s_nop 0
	v_or_b32_e32 v112, 16, v146
	v_ashrrev_i32_e32 v113, 31, v112
	v_lshl_add_u64 v[114:115], v[112:113], 2, s[92:93]
	v_mov_b32_e32 v114, v230
	v_mov_b32_e32 v115, v114
	s_and_saveexec_b64 s[8:9], vcc
	s_cbranch_execz .LBB0_106
	v_readlane_b32 s30, v246, 36
	v_mov_b32_e32 v116, v114
	v_mov_b32_e32 v117, v114
	v_pk_mul_f32 v[108:109], v[108:109], v[114:115]
	v_readlane_b32 s31, v246, 37
	v_pk_mul_f32 v[110:111], v[110:111], v[116:117]
	v_pk_mul_f32 v[116:117], v[106:107], v[116:117]
	v_pk_mul_f32 v[106:107], v[104:105], v[114:115]
	v_cvt_pk_bf16_f32 v104, v108, v109
	v_mov_b64_e32 v[108:109], s[30:31]
	v_mad_i64_i32 v[108:109], s[30:31], v112, s28, v[108:109]
	v_cvt_pk_bf16_f32 v105, v110, v111
	v_cvt_pk_bf16_f32 v106, v106, v107
	v_cvt_pk_bf16_f32 v107, v116, v117
	v_lshl_add_u64 v[108:109], v[144:145], 1, v[108:109]
	global_store_dwordx4 v[108:109], v[104:107], off

.LBB0_108:
	s_or_b64 exec, exec, s[8:9]
	s_nop 0
	v_or_b32_e32 v96, 32, v146
	v_ashrrev_i32_e32 v97, 31, v96
	v_lshl_add_u64 v[98:99], v[96:97], 2, s[92:93]
	v_mov_b32_e32 v98, v231
	v_mov_b32_e32 v99, v98
	s_and_saveexec_b64 s[8:9], vcc
	s_cbranch_execz .LBB0_110
	v_readlane_b32 s30, v246, 36
	v_mov_b32_e32 v100, v98
	v_mov_b32_e32 v101, v98
	v_pk_mul_f32 v[92:93], v[92:93], v[98:99]
	v_readlane_b32 s31, v246, 37
	v_pk_mul_f32 v[94:95], v[94:95], v[100:101]
	v_pk_mul_f32 v[100:101], v[90:91], v[100:101]
	v_pk_mul_f32 v[90:91], v[88:89], v[98:99]
	v_cvt_pk_bf16_f32 v88, v92, v93
	v_mov_b64_e32 v[92:93], s[30:31]
	v_mad_i64_i32 v[92:93], s[30:31], v96, s28, v[92:93]
	v_cvt_pk_bf16_f32 v89, v94, v95
	v_cvt_pk_bf16_f32 v90, v90, v91
	v_cvt_pk_bf16_f32 v91, v100, v101
	v_lshl_add_u64 v[92:93], v[144:145], 1, v[92:93]
	global_store_dwordx4 v[92:93], v[88:91], off

.LBB0_112:
	s_or_b64 exec, exec, s[8:9]
	s_nop 0
	v_or_b32_e32 v80, 48, v146
	v_ashrrev_i32_e32 v81, 31, v80
	v_lshl_add_u64 v[82:83], v[80:81], 2, s[92:93]
	v_mov_b32_e32 v82, v232
	v_mov_b32_e32 v83, v82
	s_and_saveexec_b64 s[8:9], vcc
	s_cbranch_execz .LBB0_114
	v_readlane_b32 s30, v246, 36
	v_mov_b32_e32 v84, v82
	v_mov_b32_e32 v85, v82
	v_pk_mul_f32 v[76:77], v[76:77], v[82:83]
	v_readlane_b32 s31, v246, 37
	v_pk_mul_f32 v[78:79], v[78:79], v[84:85]
	v_pk_mul_f32 v[84:85], v[74:75], v[84:85]
	v_pk_mul_f32 v[74:75], v[72:73], v[82:83]
	v_cvt_pk_bf16_f32 v72, v76, v77
	v_mov_b64_e32 v[76:77], s[30:31]
	v_mad_i64_i32 v[76:77], s[30:31], v80, s28, v[76:77]
	v_cvt_pk_bf16_f32 v73, v78, v79
	v_cvt_pk_bf16_f32 v74, v74, v75
	v_cvt_pk_bf16_f32 v75, v84, v85
	v_lshl_add_u64 v[76:77], v[144:145], 1, v[76:77]
	global_store_dwordx4 v[76:77], v[72:75], off

.LBB0_116:
	s_or_b64 exec, exec, s[8:9]
	s_nop 0
	v_mov_b32_e32 v64, v233
	v_add_u32_e32 v66, 0x80, v146
	v_mov_b32_e32 v65, v64
	s_and_saveexec_b64 s[8:9], vcc
	s_cbranch_execz .LBB0_118
	v_readlane_b32 s30, v246, 36
	v_mov_b32_e32 v68, v64
	v_mov_b32_e32 v69, v64
	v_pk_mul_f32 v[60:61], v[60:61], v[64:65]
	v_readlane_b32 s31, v246, 37
	v_pk_mul_f32 v[62:63], v[62:63], v[68:69]
	v_pk_mul_f32 v[68:69], v[58:59], v[68:69]
	v_pk_mul_f32 v[58:59], v[56:57], v[64:65]
	v_cvt_pk_bf16_f32 v56, v60, v61
	v_mov_b64_e32 v[60:61], s[30:31]
	v_mad_i64_i32 v[60:61], s[30:31], v66, s28, v[60:61]
	v_cvt_pk_bf16_f32 v57, v62, v63
	v_cvt_pk_bf16_f32 v58, v58, v59
	v_cvt_pk_bf16_f32 v59, v68, v69
	v_lshl_add_u64 v[60:61], v[144:145], 1, v[60:61]
	global_store_dwordx4 v[60:61], v[56:59], off

.LBB0_120:
	s_or_b64 exec, exec, s[8:9]
	s_nop 0
	v_mov_b32_e32 v48, v234
	v_add_u32_e32 v50, 0x90, v146
	v_mov_b32_e32 v49, v48
	s_and_saveexec_b64 s[8:9], vcc
	s_cbranch_execz .LBB0_122
	v_readlane_b32 s30, v246, 36
	v_mov_b32_e32 v52, v48
	v_mov_b32_e32 v53, v48
	v_pk_mul_f32 v[44:45], v[44:45], v[48:49]
	v_readlane_b32 s31, v246, 37
	v_pk_mul_f32 v[46:47], v[46:47], v[52:53]
	v_pk_mul_f32 v[52:53], v[42:43], v[52:53]
	v_pk_mul_f32 v[42:43], v[40:41], v[48:49]
	v_cvt_pk_bf16_f32 v40, v44, v45
	v_mov_b64_e32 v[44:45], s[30:31]
	v_mad_i64_i32 v[44:45], s[30:31], v50, s28, v[44:45]
	v_cvt_pk_bf16_f32 v41, v46, v47
	v_cvt_pk_bf16_f32 v42, v42, v43
	v_cvt_pk_bf16_f32 v43, v52, v53
	v_lshl_add_u64 v[44:45], v[144:145], 1, v[44:45]
	global_store_dwordx4 v[44:45], v[40:43], off

.LBB0_124:
	s_or_b64 exec, exec, s[8:9]
	s_nop 0
	v_mov_b32_e32 v32, v235
	v_add_u32_e32 v34, 0xa0, v146
	v_mov_b32_e32 v33, v32
	s_and_saveexec_b64 s[8:9], vcc
	s_cbranch_execz .LBB0_126
	v_readlane_b32 s30, v246, 36
	v_mov_b32_e32 v36, v32
	v_mov_b32_e32 v37, v32
	v_pk_mul_f32 v[28:29], v[28:29], v[32:33]
	v_readlane_b32 s31, v246, 37
	v_pk_mul_f32 v[30:31], v[30:31], v[36:37]
	v_pk_mul_f32 v[36:37], v[26:27], v[36:37]
	v_pk_mul_f32 v[26:27], v[24:25], v[32:33]
	v_cvt_pk_bf16_f32 v24, v28, v29
	v_mov_b64_e32 v[28:29], s[30:31]
	v_mad_i64_i32 v[28:29], s[30:31], v34, s28, v[28:29]
	v_cvt_pk_bf16_f32 v25, v30, v31
	v_cvt_pk_bf16_f32 v26, v26, v27
	v_cvt_pk_bf16_f32 v27, v36, v37
	v_lshl_add_u64 v[28:29], v[144:145], 1, v[28:29]
	global_store_dwordx4 v[28:29], v[24:27], off

.LBB0_128:
	s_or_b64 exec, exec, s[8:9]
	s_nop 0
	v_mov_b32_e32 v16, v236
	v_add_u32_e32 v18, 0xb0, v146
	v_mov_b32_e32 v17, v16
	s_and_saveexec_b64 s[8:9], vcc
	s_cbranch_execz .LBB0_131
	v_readlane_b32 s30, v246, 36
	v_mov_b32_e32 v20, v16
	v_mov_b32_e32 v21, v16
	v_pk_mul_f32 v[12:13], v[12:13], v[16:17]
	v_readlane_b32 s31, v246, 37
	v_pk_mul_f32 v[14:15], v[14:15], v[20:21]
	v_pk_mul_f32 v[20:21], v[10:11], v[20:21]
	v_pk_mul_f32 v[10:11], v[8:9], v[16:17]
	v_cvt_pk_bf16_f32 v8, v12, v13
	v_mov_b64_e32 v[12:13], s[30:31]
	v_mad_i64_i32 v[12:13], s[30:31], v18, s28, v[12:13]
	v_cvt_pk_bf16_f32 v9, v14, v15
	v_cvt_pk_bf16_f32 v10, v10, v11
	v_cvt_pk_bf16_f32 v11, v20, v21
	v_lshl_add_u64 v[12:13], v[144:145], 1, v[12:13]
	global_store_dwordx4 v[12:13], v[8:11], off
	s_or_b64 exec, exec, s[8:9]
	s_and_saveexec_b64 s[8:9], s[4:5]
	s_cbranch_execnz .LBB0_132

.LBB0_885:
	v_lshl_add_u32 v228, s6, 8, v152
	v_lshlrev_b32_e32 v228, 2, v228
	global_load_dword v229, v228, s[86:87]
	global_load_dword v230, v228, s[86:87] offset:64
	global_load_dword v231, v228, s[86:87] offset:128
	global_load_dword v232, v228, s[86:87] offset:192
	global_load_dword v233, v228, s[86:87] offset:512
	global_load_dword v234, v228, s[86:87] offset:576
	global_load_dword v235, v228, s[86:87] offset:640
	global_load_dword v236, v228, s[86:87] offset:704
	s_add_i32 s38, s38, 1
	s_mul_i32 s4, s38, s41
	s_mul_hi_u32 s5, s38, s65
	s_add_i32 s5, s5, s4
	s_mul_i32 s4, s38, s65
	s_add_u32 s10, s4, s64
	s_addc_u32 s11, s5, s29
	v_cmp_gt_i64_e32 vcc, s[10:11], v[142:143]
	v_cmp_lt_i64_e64 s[4:5], s[10:11], v[140:141]
	s_cbranch_vccnz .LBB0_887
	s_ashr_i32 s11, s10, 31
	s_lshr_b32 s11, s11, 29
	s_add_i32 s11, s10, s11
	s_ashr_i32 s14, s11, 3
	s_and_b32 s11, s11, -8
	s_sub_i32 s10, s10, s11
	s_cmp_lt_i32 s10, 0
	s_cselect_b32 s11, s30, 0x160
	s_mul_i32 s10, s10, s11
	s_add_i32 s10, s10, s14
	s_mul_hi_i32 s11, s10, 0x2e8ba2e9
	s_lshr_b32 s14, s11, 31
	s_ashr_i32 s11, s11, 6
	s_add_i32 s11, s11, s14
	s_lshl_b32 s15, s11, 3
	s_sub_i32 s14, 64, s15
	s_min_i32 s16, s14, 8
	s_abs_i32 s14, s16
	v_cvt_f32_u32_e32 v0, s14
	s_sub_i32 s18, 0, s14
	s_mulk_i32 s11, 0x160
	s_sub_i32 s10, s10, s11
	v_rcp_iflag_f32_e32 v0, v0
	s_abs_i32 s11, s10
	s_xor_b32 s17, s10, s16
	s_ashr_i32 s17, s17, 31
	v_mul_f32_e32 v0, 0x4f7ffffe, v0
	v_cvt_u32_f32_e32 v0, v0
	s_nop 0
	v_readfirstlane_b32 s19, v0
	s_mul_i32 s18, s18, s19
	s_mul_hi_u32 s18, s19, s18
	s_add_i32 s19, s19, s18
	s_mul_hi_u32 s18, s11, s19
	s_mul_i32 s19, s18, s14
	s_sub_i32 s11, s11, s19
	s_add_i32 s22, s18, 1
	s_sub_i32 s19, s11, s14
	s_cmp_ge_u32 s11, s14
	s_cselect_b32 s18, s22, s18
	s_cselect_b32 s11, s19, s11
	s_add_i32 s19, s18, 1
	s_cmp_ge_u32 s11, s14
	s_cselect_b32 s11, s19, s18
	s_xor_b32 s11, s11, s17
	s_sub_i32 s14, s11, s17
	s_mul_i32 s11, s14, s16
	s_sub_i32 s10, s10, s11
	s_add_i32 s16, s15, s10

.LBB0_891:
	v_lshl_add_u32 v144, s6, 8, v152
	v_ashrrev_i32_e32 v145, 31, v144
	v_lshl_add_u64 v[150:151], v[144:145], 2, s[86:87]
	s_nop 0
	v_or_b32_e32 v162, 16, v144
	v_ashrrev_i32_e32 v163, 31, v162
	v_lshl_add_u64 v[164:165], v[162:163], 2, s[86:87]
	v_lshl_or_b32 v148, s7, 7, v154
	v_readlane_b32 s6, v246, 36
	v_readlane_b32 s7, v246, 37
	v_ashrrev_i32_e32 v149, 31, v148
	v_lshlrev_b64 v[148:149], 1, v[148:149]
	v_mov_b64_e32 v[146:147], s[6:7]
	v_mad_i64_i32 v[160:161], s[6:7], v144, s45, v[146:147]
	v_lshl_add_u64 v[160:161], v[160:161], 0, v[148:149]
	v_fmamk_f32 v145, v229, 0x3a000000, v158
	v_mul_f32_e32 v159, 0x4b800000, v145
	v_cmp_gt_f32_e32 vcc, s44, v145
	s_nop 1
	v_cndmask_b32_e32 v145, v145, v159, vcc
	v_rsq_f32_e32 v145, v145
	s_nop 0
	v_mul_f32_e32 v159, 0x45800000, v145
	v_cndmask_b32_e32 v166, v145, v159, vcc
	v_pk_mul_f32 v[124:125], v[124:125], v[166:167] op_sel_hi:[1,0]
	v_pk_mul_f32 v[126:127], v[126:127], v[166:167] op_sel_hi:[1,0]
	v_pk_mul_f32 v[120:121], v[120:121], v[166:167] op_sel_hi:[1,0]
	v_pk_mul_f32 v[122:123], v[122:123], v[166:167] op_sel_hi:[1,0]
	v_pk_mul_f32 v[116:117], v[116:117], v[166:167] op_sel_hi:[1,0]
	v_pk_mul_f32 v[118:119], v[118:119], v[166:167] op_sel_hi:[1,0]
	v_pk_mul_f32 v[112:113], v[112:113], v[166:167] op_sel_hi:[1,0]
	v_pk_mul_f32 v[114:115], v[114:115], v[166:167] op_sel_hi:[1,0]
	v_mul_f32_e32 v145, 0xbfb8aa3b, v124
	v_mul_f32_e32 v159, 0xbfb8aa3b, v125
	v_mul_f32_e32 v163, 0xbfb8aa3b, v126
	v_mul_f32_e32 v166, 0xbfb8aa3b, v127
	v_mul_f32_e32 v167, 0xbfb8aa3b, v120
	v_mul_f32_e32 v168, 0xbfb8aa3b, v121
	v_mul_f32_e32 v169, 0xbfb8aa3b, v122
	v_mul_f32_e32 v170, 0xbfb8aa3b, v123
	v_exp_f32_e32 v145, v145
	v_exp_f32_e32 v159, v159
	v_exp_f32_e32 v163, v163
	v_exp_f32_e32 v166, v166
	v_exp_f32_e32 v167, v167
	v_exp_f32_e32 v168, v168
	v_exp_f32_e32 v169, v169
	v_exp_f32_e32 v170, v170
	v_add_f32_e32 v145, 1.0, v145
	v_add_f32_e32 v159, 1.0, v159
	v_add_f32_e32 v163, 1.0, v163
	v_add_f32_e32 v171, 1.0, v166
	v_add_f32_e32 v172, 1.0, v167
	v_add_f32_e32 v173, 1.0, v168
	v_add_f32_e32 v174, 1.0, v169
	v_add_f32_e32 v175, 1.0, v170
	v_rcp_f32_e32 v166, v145
	v_rcp_f32_e32 v167, v159
	v_rcp_f32_e32 v168, v163
	v_rcp_f32_e32 v169, v171
	v_rcp_f32_e32 v170, v172
	v_rcp_f32_e32 v171, v173
	v_rcp_f32_e32 v172, v174
	v_rcp_f32_e32 v173, v175
	v_pk_mul_f32 v[124:125], v[124:125], v[166:167]
	v_pk_mul_f32 v[126:127], v[126:127], v[168:169]
	v_pk_mul_f32 v[120:121], v[120:121], v[170:171]
	v_pk_mul_f32 v[122:123], v[122:123], v[172:173]
	v_pk_mul_f32 v[116:117], v[116:117], v[124:125]
	v_pk_mul_f32 v[118:119], v[118:119], v[126:127]
	v_pk_mul_f32 v[120:121], v[112:113], v[120:121]
	v_pk_mul_f32 v[122:123], v[114:115], v[122:123]
	v_cvt_pk_bf16_f32 v112, v116, v117
	v_cvt_pk_bf16_f32 v113, v118, v119
	v_cvt_pk_bf16_f32 v114, v120, v121
	v_cvt_pk_bf16_f32 v115, v122, v123
	global_store_dwordx4 v[160:161], v[112:115], off nt
	s_nop 0
	s_nop 0
	v_or_b32_e32 v112, 32, v144
	v_mad_i64_i32 v[114:115], s[6:7], v162, s45, v[146:147]
	v_lshl_add_u64 v[114:115], v[114:115], 0, v[148:149]
	v_fmamk_f32 v113, v230, 0x3a000000, v158
	v_mul_f32_e32 v116, 0x4b800000, v113
	v_cmp_gt_f32_e32 vcc, s44, v113
	s_nop 1
	v_cndmask_b32_e32 v113, v113, v116, vcc
	v_rsq_f32_e32 v118, v113
	v_ashrrev_i32_e32 v113, 31, v112
	v_lshl_add_u64 v[116:117], v[112:113], 2, s[86:87]
	v_mul_f32_e32 v113, 0x45800000, v118
	v_cndmask_b32_e32 v118, v118, v113, vcc
	v_pk_mul_f32 v[108:109], v[108:109], v[118:119] op_sel_hi:[1,0]
	v_pk_mul_f32 v[110:111], v[110:111], v[118:119] op_sel_hi:[1,0]
	v_pk_mul_f32 v[104:105], v[104:105], v[118:119] op_sel_hi:[1,0]
	v_pk_mul_f32 v[106:107], v[106:107], v[118:119] op_sel_hi:[1,0]
	v_pk_mul_f32 v[100:101], v[100:101], v[118:119] op_sel_hi:[1,0]
	v_pk_mul_f32 v[102:103], v[102:103], v[118:119] op_sel_hi:[1,0]
	v_pk_mul_f32 v[96:97], v[96:97], v[118:119] op_sel_hi:[1,0]
	v_pk_mul_f32 v[98:99], v[98:99], v[118:119] op_sel_hi:[1,0]
	v_mul_f32_e32 v113, 0xbfb8aa3b, v108
	v_mul_f32_e32 v118, 0xbfb8aa3b, v109
	v_mul_f32_e32 v119, 0xbfb8aa3b, v110
	v_mul_f32_e32 v120, 0xbfb8aa3b, v111
	v_mul_f32_e32 v121, 0xbfb8aa3b, v104
	v_mul_f32_e32 v122, 0xbfb8aa3b, v105
	v_mul_f32_e32 v123, 0xbfb8aa3b, v106
	v_mul_f32_e32 v124, 0xbfb8aa3b, v107
	v_exp_f32_e32 v113, v113
	v_exp_f32_e32 v118, v118
	v_exp_f32_e32 v119, v119
	v_exp_f32_e32 v120, v120
	v_exp_f32_e32 v121, v121
	v_exp_f32_e32 v122, v122
	v_exp_f32_e32 v123, v123
	v_exp_f32_e32 v124, v124
	v_add_f32_e32 v113, 1.0, v113
	v_add_f32_e32 v125, 1.0, v118
	v_add_f32_e32 v126, 1.0, v119
	v_add_f32_e32 v127, 1.0, v120
	v_add_f32_e32 v145, 1.0, v121
	v_add_f32_e32 v159, 1.0, v122
	v_add_f32_e32 v160, 1.0, v123
	v_add_f32_e32 v161, 1.0, v124
	v_rcp_f32_e32 v118, v113
	v_rcp_f32_e32 v119, v125
	v_rcp_f32_e32 v120, v126
	v_rcp_f32_e32 v121, v127
	v_rcp_f32_e32 v122, v145
	v_rcp_f32_e32 v123, v159
	v_rcp_f32_e32 v124, v160
	v_rcp_f32_e32 v125, v161
	v_pk_mul_f32 v[108:109], v[108:109], v[118:119]
	v_pk_mul_f32 v[110:111], v[110:111], v[120:121]
	v_pk_mul_f32 v[104:105], v[104:105], v[122:123]
	v_pk_mul_f32 v[106:107], v[106:107], v[124:125]
	v_pk_mul_f32 v[100:101], v[100:101], v[108:109]
	v_pk_mul_f32 v[102:103], v[102:103], v[110:111]
	v_pk_mul_f32 v[104:105], v[96:97], v[104:105]
	v_pk_mul_f32 v[106:107], v[98:99], v[106:107]
	v_cvt_pk_bf16_f32 v96, v100, v101
	v_cvt_pk_bf16_f32 v97, v102, v103
	v_cvt_pk_bf16_f32 v98, v104, v105
	v_cvt_pk_bf16_f32 v99, v106, v107
	global_store_dwordx4 v[114:115], v[96:99], off nt
	s_nop 0
	s_nop 0
	v_or_b32_e32 v96, 48, v144
	v_mad_i64_i32 v[98:99], s[6:7], v112, s45, v[146:147]
	v_lshl_add_u64 v[98:99], v[98:99], 0, v[148:149]
	v_fmamk_f32 v97, v231, 0x3a000000, v158
	v_mul_f32_e32 v100, 0x4b800000, v97
	v_cmp_gt_f32_e32 vcc, s44, v97
	s_nop 1
	v_cndmask_b32_e32 v97, v97, v100, vcc
	v_rsq_f32_e32 v102, v97
	v_ashrrev_i32_e32 v97, 31, v96
	v_lshl_add_u64 v[100:101], v[96:97], 2, s[86:87]
	v_mul_f32_e32 v97, 0x45800000, v102
	v_cndmask_b32_e32 v102, v102, v97, vcc
	v_pk_mul_f32 v[92:93], v[92:93], v[102:103] op_sel_hi:[1,0]
	v_pk_mul_f32 v[94:95], v[94:95], v[102:103] op_sel_hi:[1,0]
	v_pk_mul_f32 v[88:89], v[88:89], v[102:103] op_sel_hi:[1,0]
	v_pk_mul_f32 v[90:91], v[90:91], v[102:103] op_sel_hi:[1,0]
	v_pk_mul_f32 v[84:85], v[84:85], v[102:103] op_sel_hi:[1,0]
	v_pk_mul_f32 v[86:87], v[86:87], v[102:103] op_sel_hi:[1,0]
	v_pk_mul_f32 v[80:81], v[80:81], v[102:103] op_sel_hi:[1,0]
	v_pk_mul_f32 v[82:83], v[82:83], v[102:103] op_sel_hi:[1,0]
	v_mul_f32_e32 v97, 0xbfb8aa3b, v92
	v_mul_f32_e32 v102, 0xbfb8aa3b, v93
	v_mul_f32_e32 v103, 0xbfb8aa3b, v94
	v_mul_f32_e32 v104, 0xbfb8aa3b, v95
	v_mul_f32_e32 v105, 0xbfb8aa3b, v88
	v_mul_f32_e32 v106, 0xbfb8aa3b, v89
	v_mul_f32_e32 v107, 0xbfb8aa3b, v90
	v_mul_f32_e32 v108, 0xbfb8aa3b, v91
	v_exp_f32_e32 v97, v97
	v_exp_f32_e32 v102, v102
	v_exp_f32_e32 v103, v103
	v_exp_f32_e32 v104, v104
	v_exp_f32_e32 v105, v105
	v_exp_f32_e32 v106, v106
	v_exp_f32_e32 v107, v107
	v_exp_f32_e32 v108, v108
	v_add_f32_e32 v97, 1.0, v97
	v_add_f32_e32 v109, 1.0, v102
	v_add_f32_e32 v110, 1.0, v103
	v_add_f32_e32 v111, 1.0, v104
	v_add_f32_e32 v112, 1.0, v105
	v_add_f32_e32 v113, 1.0, v106
	v_add_f32_e32 v114, 1.0, v107
	v_add_f32_e32 v115, 1.0, v108
	v_rcp_f32_e32 v102, v97
	v_rcp_f32_e32 v103, v109
	v_rcp_f32_e32 v104, v110
	v_rcp_f32_e32 v105, v111
	v_rcp_f32_e32 v106, v112
	v_rcp_f32_e32 v107, v113
	v_rcp_f32_e32 v108, v114
	v_rcp_f32_e32 v109, v115
	v_pk_mul_f32 v[92:93], v[92:93], v[102:103]
	v_pk_mul_f32 v[94:95], v[94:95], v[104:105]
	v_pk_mul_f32 v[88:89], v[88:89], v[106:107]
	v_pk_mul_f32 v[90:91], v[90:91], v[108:109]
	v_pk_mul_f32 v[84:85], v[84:85], v[92:93]
	v_pk_mul_f32 v[86:87], v[86:87], v[94:95]
	v_pk_mul_f32 v[88:89], v[80:81], v[88:89]
	v_pk_mul_f32 v[90:91], v[82:83], v[90:91]
	v_cvt_pk_bf16_f32 v80, v84, v85
	v_cvt_pk_bf16_f32 v81, v86, v87
	v_cvt_pk_bf16_f32 v82, v88, v89
	v_cvt_pk_bf16_f32 v83, v90, v91
	global_store_dwordx4 v[98:99], v[80:83], off nt
	s_nop 1
	v_fmamk_f32 v80, v232, 0x3a000000, v158
	v_mul_f32_e32 v81, 0x4b800000, v80
	v_cmp_gt_f32_e32 vcc, s44, v80
	s_nop 1
	v_cndmask_b32_e32 v80, v80, v81, vcc
	v_rsq_f32_e32 v82, v80
	v_mad_i64_i32 v[80:81], s[6:7], v96, s45, v[146:147]
	v_lshl_add_u64 v[80:81], v[80:81], 0, v[148:149]
	v_mul_f32_e32 v83, 0x45800000, v82
	v_cndmask_b32_e32 v82, v82, v83, vcc
	v_pk_mul_f32 v[76:77], v[76:77], v[82:83] op_sel_hi:[1,0]
	v_pk_mul_f32 v[78:79], v[78:79], v[82:83] op_sel_hi:[1,0]
	v_pk_mul_f32 v[72:73], v[72:73], v[82:83] op_sel_hi:[1,0]
	v_pk_mul_f32 v[74:75], v[74:75], v[82:83] op_sel_hi:[1,0]
	v_pk_mul_f32 v[68:69], v[68:69], v[82:83] op_sel_hi:[1,0]
	v_pk_mul_f32 v[70:71], v[70:71], v[82:83] op_sel_hi:[1,0]
	v_pk_mul_f32 v[64:65], v[64:65], v[82:83] op_sel_hi:[1,0]
	v_pk_mul_f32 v[66:67], v[66:67], v[82:83] op_sel_hi:[1,0]
	v_mul_f32_e32 v82, 0xbfb8aa3b, v76
	v_mul_f32_e32 v83, 0xbfb8aa3b, v77
	v_mul_f32_e32 v84, 0xbfb8aa3b, v78
	v_mul_f32_e32 v85, 0xbfb8aa3b, v79
	v_mul_f32_e32 v86, 0xbfb8aa3b, v72
	v_mul_f32_e32 v87, 0xbfb8aa3b, v73
	v_mul_f32_e32 v88, 0xbfb8aa3b, v74
	v_mul_f32_e32 v89, 0xbfb8aa3b, v75
	v_exp_f32_e32 v82, v82
	v_exp_f32_e32 v83, v83
	v_exp_f32_e32 v84, v84
	v_exp_f32_e32 v85, v85
	v_exp_f32_e32 v86, v86
	v_exp_f32_e32 v87, v87
	v_exp_f32_e32 v88, v88
	v_exp_f32_e32 v89, v89
	v_add_f32_e32 v82, 1.0, v82
	v_add_f32_e32 v83, 1.0, v83
	v_add_f32_e32 v84, 1.0, v84
	v_add_f32_e32 v85, 1.0, v85
	v_add_f32_e32 v86, 1.0, v86
	v_add_f32_e32 v87, 1.0, v87
	v_add_f32_e32 v88, 1.0, v88
	v_add_f32_e32 v89, 1.0, v89
	v_rcp_f32_e32 v82, v82
	v_rcp_f32_e32 v83, v83
	v_rcp_f32_e32 v84, v84
	v_rcp_f32_e32 v85, v85
	v_rcp_f32_e32 v86, v86
	v_rcp_f32_e32 v87, v87
	v_rcp_f32_e32 v88, v88
	v_rcp_f32_e32 v89, v89
	v_pk_mul_f32 v[76:77], v[76:77], v[82:83]
	v_pk_mul_f32 v[78:79], v[78:79], v[84:85]
	v_pk_mul_f32 v[72:73], v[72:73], v[86:87]
	v_pk_mul_f32 v[74:75], v[74:75], v[88:89]
	v_pk_mul_f32 v[68:69], v[68:69], v[76:77]
	v_pk_mul_f32 v[70:71], v[70:71], v[78:79]
	v_pk_mul_f32 v[72:73], v[64:65], v[72:73]
	v_pk_mul_f32 v[74:75], v[66:67], v[74:75]
	v_cvt_pk_bf16_f32 v64, v68, v69
	v_cvt_pk_bf16_f32 v65, v70, v71
	v_cvt_pk_bf16_f32 v66, v72, v73
	v_cvt_pk_bf16_f32 v67, v74, v75
	global_store_dwordx4 v[80:81], v[64:67], off nt
	s_nop 0
	s_nop 0
	v_add_u32_e32 v65, 0x80, v144
	v_fmamk_f32 v64, v233, 0x3a000000, v158
	v_mul_f32_e32 v66, 0x4b800000, v64
	v_cmp_gt_f32_e32 vcc, s44, v64
	s_nop 1
	v_cndmask_b32_e32 v64, v64, v66, vcc
	v_rsq_f32_e32 v66, v64
	v_mad_i64_i32 v[64:65], s[6:7], v65, s45, v[146:147]
	v_lshl_add_u64 v[64:65], v[64:65], 0, v[148:149]
	v_mul_f32_e32 v67, 0x45800000, v66
	v_cndmask_b32_e32 v66, v66, v67, vcc
	v_pk_mul_f32 v[60:61], v[60:61], v[66:67] op_sel_hi:[1,0]
	v_pk_mul_f32 v[62:63], v[62:63], v[66:67] op_sel_hi:[1,0]
	v_pk_mul_f32 v[56:57], v[56:57], v[66:67] op_sel_hi:[1,0]
	v_pk_mul_f32 v[58:59], v[58:59], v[66:67] op_sel_hi:[1,0]
	v_pk_mul_f32 v[52:53], v[52:53], v[66:67] op_sel_hi:[1,0]
	v_pk_mul_f32 v[54:55], v[54:55], v[66:67] op_sel_hi:[1,0]
	v_pk_mul_f32 v[48:49], v[48:49], v[66:67] op_sel_hi:[1,0]
	v_pk_mul_f32 v[50:51], v[50:51], v[66:67] op_sel_hi:[1,0]
	v_mul_f32_e32 v66, 0xbfb8aa3b, v60
	v_mul_f32_e32 v67, 0xbfb8aa3b, v61
	v_mul_f32_e32 v68, 0xbfb8aa3b, v62
	v_mul_f32_e32 v69, 0xbfb8aa3b, v63
	v_mul_f32_e32 v70, 0xbfb8aa3b, v56
	v_mul_f32_e32 v71, 0xbfb8aa3b, v57
	v_mul_f32_e32 v72, 0xbfb8aa3b, v58
	v_mul_f32_e32 v73, 0xbfb8aa3b, v59
	v_exp_f32_e32 v66, v66
	v_exp_f32_e32 v67, v67
	v_exp_f32_e32 v68, v68
	v_exp_f32_e32 v69, v69
	v_exp_f32_e32 v70, v70
	v_exp_f32_e32 v71, v71
	v_exp_f32_e32 v72, v72
	v_exp_f32_e32 v73, v73
	v_add_f32_e32 v66, 1.0, v66
	v_add_f32_e32 v67, 1.0, v67
	v_add_f32_e32 v68, 1.0, v68
	v_add_f32_e32 v69, 1.0, v69
	v_add_f32_e32 v70, 1.0, v70
	v_add_f32_e32 v71, 1.0, v71
	v_add_f32_e32 v72, 1.0, v72
	v_add_f32_e32 v73, 1.0, v73
	v_rcp_f32_e32 v66, v66
	v_rcp_f32_e32 v67, v67
	v_rcp_f32_e32 v68, v68
	v_rcp_f32_e32 v69, v69
	v_rcp_f32_e32 v70, v70
	v_rcp_f32_e32 v71, v71
	v_rcp_f32_e32 v72, v72
	v_rcp_f32_e32 v73, v73
	v_pk_mul_f32 v[60:61], v[60:61], v[66:67]
	v_pk_mul_f32 v[62:63], v[62:63], v[68:69]
	v_pk_mul_f32 v[56:57], v[56:57], v[70:71]
	v_pk_mul_f32 v[58:59], v[58:59], v[72:73]
	v_pk_mul_f32 v[52:53], v[52:53], v[60:61]
	v_pk_mul_f32 v[54:55], v[54:55], v[62:63]
	v_pk_mul_f32 v[56:57], v[48:49], v[56:57]
	v_pk_mul_f32 v[58:59], v[50:51], v[58:59]
	v_cvt_pk_bf16_f32 v48, v52, v53
	v_cvt_pk_bf16_f32 v49, v54, v55
	v_cvt_pk_bf16_f32 v50, v56, v57
	v_cvt_pk_bf16_f32 v51, v58, v59
	global_store_dwordx4 v[64:65], v[48:51], off nt
	s_nop 0
	s_nop 0
	v_add_u32_e32 v49, 0x90, v144
	v_fmamk_f32 v48, v234, 0x3a000000, v158
	v_mul_f32_e32 v50, 0x4b800000, v48
	v_cmp_gt_f32_e32 vcc, s44, v48
	s_nop 1
	v_cndmask_b32_e32 v48, v48, v50, vcc
	v_rsq_f32_e32 v50, v48
	v_mad_i64_i32 v[48:49], s[6:7], v49, s45, v[146:147]
	v_lshl_add_u64 v[48:49], v[48:49], 0, v[148:149]
	v_mul_f32_e32 v51, 0x45800000, v50
	v_cndmask_b32_e32 v50, v50, v51, vcc
	v_pk_mul_f32 v[44:45], v[44:45], v[50:51] op_sel_hi:[1,0]
	v_pk_mul_f32 v[46:47], v[46:47], v[50:51] op_sel_hi:[1,0]
	v_pk_mul_f32 v[40:41], v[40:41], v[50:51] op_sel_hi:[1,0]
	v_pk_mul_f32 v[42:43], v[42:43], v[50:51] op_sel_hi:[1,0]
	v_pk_mul_f32 v[36:37], v[36:37], v[50:51] op_sel_hi:[1,0]
	v_pk_mul_f32 v[38:39], v[38:39], v[50:51] op_sel_hi:[1,0]
	v_pk_mul_f32 v[32:33], v[32:33], v[50:51] op_sel_hi:[1,0]
	v_pk_mul_f32 v[34:35], v[34:35], v[50:51] op_sel_hi:[1,0]
	v_mul_f32_e32 v50, 0xbfb8aa3b, v44
	v_mul_f32_e32 v51, 0xbfb8aa3b, v45
	v_mul_f32_e32 v52, 0xbfb8aa3b, v46
	v_mul_f32_e32 v53, 0xbfb8aa3b, v47
	v_mul_f32_e32 v54, 0xbfb8aa3b, v40
	v_mul_f32_e32 v55, 0xbfb8aa3b, v41
	v_mul_f32_e32 v56, 0xbfb8aa3b, v42
	v_mul_f32_e32 v57, 0xbfb8aa3b, v43
	v_exp_f32_e32 v50, v50
	v_exp_f32_e32 v51, v51
	v_exp_f32_e32 v52, v52
	v_exp_f32_e32 v53, v53
	v_exp_f32_e32 v54, v54
	v_exp_f32_e32 v55, v55
	v_exp_f32_e32 v56, v56
	v_exp_f32_e32 v57, v57
	v_add_f32_e32 v50, 1.0, v50
	v_add_f32_e32 v51, 1.0, v51
	v_add_f32_e32 v52, 1.0, v52
	v_add_f32_e32 v53, 1.0, v53
	v_add_f32_e32 v54, 1.0, v54
	v_add_f32_e32 v55, 1.0, v55
	v_add_f32_e32 v56, 1.0, v56
	v_add_f32_e32 v57, 1.0, v57
	v_rcp_f32_e32 v50, v50
	v_rcp_f32_e32 v51, v51
	v_rcp_f32_e32 v52, v52
	v_rcp_f32_e32 v53, v53
	v_rcp_f32_e32 v54, v54
	v_rcp_f32_e32 v55, v55
	v_rcp_f32_e32 v56, v56
	v_rcp_f32_e32 v57, v57
	v_pk_mul_f32 v[44:45], v[44:45], v[50:51]
	v_pk_mul_f32 v[46:47], v[46:47], v[52:53]
	v_pk_mul_f32 v[40:41], v[40:41], v[54:55]
	v_pk_mul_f32 v[42:43], v[42:43], v[56:57]
	v_pk_mul_f32 v[36:37], v[36:37], v[44:45]
	v_pk_mul_f32 v[38:39], v[38:39], v[46:47]
	v_pk_mul_f32 v[40:41], v[32:33], v[40:41]
	v_pk_mul_f32 v[42:43], v[34:35], v[42:43]
	v_cvt_pk_bf16_f32 v32, v36, v37
	v_cvt_pk_bf16_f32 v33, v38, v39
	v_cvt_pk_bf16_f32 v34, v40, v41
	v_cvt_pk_bf16_f32 v35, v42, v43
	global_store_dwordx4 v[48:49], v[32:35], off nt
	s_nop 0
	s_nop 0
	v_add_u32_e32 v33, 0xa0, v144
	v_fmamk_f32 v32, v235, 0x3a000000, v158
	v_mul_f32_e32 v34, 0x4b800000, v32
	v_cmp_gt_f32_e32 vcc, s44, v32
	s_nop 1
	v_cndmask_b32_e32 v32, v32, v34, vcc
	v_rsq_f32_e32 v34, v32
	v_mad_i64_i32 v[32:33], s[6:7], v33, s45, v[146:147]
	v_lshl_add_u64 v[32:33], v[32:33], 0, v[148:149]
	v_mul_f32_e32 v35, 0x45800000, v34
	v_cndmask_b32_e32 v34, v34, v35, vcc
	v_pk_mul_f32 v[28:29], v[28:29], v[34:35] op_sel_hi:[1,0]
	v_pk_mul_f32 v[30:31], v[30:31], v[34:35] op_sel_hi:[1,0]
	v_pk_mul_f32 v[24:25], v[24:25], v[34:35] op_sel_hi:[1,0]
	v_pk_mul_f32 v[26:27], v[26:27], v[34:35] op_sel_hi:[1,0]
	v_pk_mul_f32 v[20:21], v[20:21], v[34:35] op_sel_hi:[1,0]
	v_pk_mul_f32 v[22:23], v[22:23], v[34:35] op_sel_hi:[1,0]
	v_pk_mul_f32 v[16:17], v[16:17], v[34:35] op_sel_hi:[1,0]
	v_pk_mul_f32 v[18:19], v[18:19], v[34:35] op_sel_hi:[1,0]
	v_mul_f32_e32 v34, 0xbfb8aa3b, v28
	v_mul_f32_e32 v35, 0xbfb8aa3b, v29
	v_mul_f32_e32 v36, 0xbfb8aa3b, v30
	v_mul_f32_e32 v37, 0xbfb8aa3b, v31
	v_mul_f32_e32 v38, 0xbfb8aa3b, v24
	v_mul_f32_e32 v39, 0xbfb8aa3b, v25
	v_mul_f32_e32 v40, 0xbfb8aa3b, v26
	v_mul_f32_e32 v41, 0xbfb8aa3b, v27
	v_exp_f32_e32 v34, v34
	v_exp_f32_e32 v35, v35
	v_exp_f32_e32 v36, v36
	v_exp_f32_e32 v37, v37
	v_exp_f32_e32 v38, v38
	v_exp_f32_e32 v39, v39
	v_exp_f32_e32 v40, v40
	v_exp_f32_e32 v41, v41
	v_add_f32_e32 v34, 1.0, v34
	v_add_f32_e32 v35, 1.0, v35
	v_add_f32_e32 v36, 1.0, v36
	v_add_f32_e32 v37, 1.0, v37
	v_add_f32_e32 v38, 1.0, v38
	v_add_f32_e32 v39, 1.0, v39
	v_add_f32_e32 v40, 1.0, v40
	v_add_f32_e32 v41, 1.0, v41
	v_rcp_f32_e32 v34, v34
	v_rcp_f32_e32 v35, v35
	v_rcp_f32_e32 v36, v36
	v_rcp_f32_e32 v37, v37
	v_rcp_f32_e32 v38, v38
	v_rcp_f32_e32 v39, v39
	v_rcp_f32_e32 v40, v40
	v_rcp_f32_e32 v41, v41
	v_pk_mul_f32 v[28:29], v[28:29], v[34:35]
	v_pk_mul_f32 v[30:31], v[30:31], v[36:37]
	v_pk_mul_f32 v[24:25], v[24:25], v[38:39]
	v_pk_mul_f32 v[26:27], v[26:27], v[40:41]
	v_pk_mul_f32 v[20:21], v[20:21], v[28:29]
	v_pk_mul_f32 v[22:23], v[22:23], v[30:31]
	v_pk_mul_f32 v[24:25], v[16:17], v[24:25]
	v_pk_mul_f32 v[26:27], v[18:19], v[26:27]
	v_cvt_pk_bf16_f32 v16, v20, v21
	v_cvt_pk_bf16_f32 v17, v22, v23
	v_cvt_pk_bf16_f32 v18, v24, v25
	v_cvt_pk_bf16_f32 v19, v26, v27
	global_store_dwordx4 v[32:33], v[16:19], off nt
	s_nop 0
	s_andn2_b64 vcc, exec, s[4:5]
	v_add_u32_e32 v17, 0xb0, v144
	s_mov_b64 s[4:5], -1
	v_fmamk_f32 v16, v236, 0x3a000000, v158
	v_mul_f32_e32 v18, 0x4b800000, v16
	v_cmp_gt_f32_e64 s[6:7], s44, v16
	s_nop 1
	v_cndmask_b32_e64 v16, v16, v18, s[6:7]
	v_rsq_f32_e32 v18, v16
	v_mad_i64_i32 v[16:17], s[10:11], v17, s45, v[146:147]
	v_lshl_add_u64 v[16:17], v[16:17], 0, v[148:149]
	v_mul_f32_e32 v19, 0x45800000, v18
	v_cndmask_b32_e64 v18, v18, v19, s[6:7]
	v_pk_mul_f32 v[12:13], v[12:13], v[18:19] op_sel_hi:[1,0]
	v_pk_mul_f32 v[14:15], v[14:15], v[18:19] op_sel_hi:[1,0]
	v_pk_mul_f32 v[8:9], v[8:9], v[18:19] op_sel_hi:[1,0]
	v_pk_mul_f32 v[10:11], v[10:11], v[18:19] op_sel_hi:[1,0]
	v_pk_mul_f32 v[4:5], v[4:5], v[18:19] op_sel_hi:[1,0]
	v_pk_mul_f32 v[6:7], v[6:7], v[18:19] op_sel_hi:[1,0]
	v_pk_mul_f32 v[0:1], v[0:1], v[18:19] op_sel_hi:[1,0]
	v_pk_mul_f32 v[2:3], v[2:3], v[18:19] op_sel_hi:[1,0]
	v_mul_f32_e32 v18, 0xbfb8aa3b, v12
	v_mul_f32_e32 v19, 0xbfb8aa3b, v13
	v_mul_f32_e32 v20, 0xbfb8aa3b, v14
	v_mul_f32_e32 v21, 0xbfb8aa3b, v15
	v_mul_f32_e32 v22, 0xbfb8aa3b, v8
	v_mul_f32_e32 v23, 0xbfb8aa3b, v9
	v_mul_f32_e32 v24, 0xbfb8aa3b, v10
	v_mul_f32_e32 v25, 0xbfb8aa3b, v11
	v_exp_f32_e32 v18, v18
	v_exp_f32_e32 v19, v19
	v_exp_f32_e32 v20, v20
	v_exp_f32_e32 v21, v21
	v_exp_f32_e32 v22, v22
	v_exp_f32_e32 v23, v23
	v_exp_f32_e32 v24, v24
	v_exp_f32_e32 v25, v25
	v_add_f32_e32 v18, 1.0, v18
	v_add_f32_e32 v19, 1.0, v19
	v_add_f32_e32 v20, 1.0, v20
	v_add_f32_e32 v21, 1.0, v21
	v_add_f32_e32 v22, 1.0, v22
	v_add_f32_e32 v23, 1.0, v23
	v_add_f32_e32 v24, 1.0, v24
	v_add_f32_e32 v25, 1.0, v25
	v_rcp_f32_e32 v18, v18
	v_rcp_f32_e32 v19, v19
	v_rcp_f32_e32 v20, v20
	v_rcp_f32_e32 v21, v21
	v_rcp_f32_e32 v22, v22
	v_rcp_f32_e32 v23, v23
	v_rcp_f32_e32 v24, v24
	v_rcp_f32_e32 v25, v25
	v_pk_mul_f32 v[12:13], v[12:13], v[18:19]
	v_pk_mul_f32 v[14:15], v[14:15], v[20:21]
	v_pk_mul_f32 v[8:9], v[8:9], v[22:23]
	v_pk_mul_f32 v[10:11], v[10:11], v[24:25]
	v_pk_mul_f32 v[4:5], v[4:5], v[12:13]
	v_pk_mul_f32 v[6:7], v[6:7], v[14:15]
	v_pk_mul_f32 v[8:9], v[0:1], v[8:9]
	v_pk_mul_f32 v[10:11], v[2:3], v[10:11]
	v_cvt_pk_bf16_f32 v0, v4, v5
	v_cvt_pk_bf16_f32 v1, v6, v7
	v_cvt_pk_bf16_f32 v2, v8, v9
	v_cvt_pk_bf16_f32 v3, v10, v11
	global_store_dwordx4 v[16:17], v[0:3], off nt
	s_cbranch_vccnz .LBB0_884
	s_andn2_b64 vcc, exec, s[0:1]
	s_cbranch_vccnz .LBB0_883
	s_barrier
	s_branch .LBB0_883
